# M3 wave-0 inclusive sum/max scans via DPP row_shr/row_bcast instead of 12 ds_bpermute round trips (on top of hand-off edit)
# speedup vs baseline: 1.0021x; 1.0010x over previous
; __device__ __forceinline__ float wave_incl_sum(float v, int lane) {
; #pragma unroll
;     for (int o = 1; o < 64; o <<= 1) { const float t = __shfl_up(v, o); if (lane >= o) v += t; }
;     return v;
; }
; __device__ __forceinline__ float wave_incl_max(float v, int lane) {
; #pragma unroll
;     for (int o = 1; o < 64; o <<= 1) { const float t = __shfl_up(v, o); if (lane >= o) v = fmaxf(v, t); }
;     return v;
; }
; __device__ __forceinline__ float log_sigmoid_f(float x) { return fminf(x, 0.f) - log1pf(expf(-fabsf(x))); }
; __device__ __forceinline__ void m3_phase(const Params& p, unsigned char* ldsg, int G) {
;     ...
;             if (wave == 0) {
;                 const float b = wave_incl_sum(log_sigmoid_f(g_fp), lane);
;                 const float uu = g_ig - b;
;                 const float U = wave_incl_max(uu, lane);
;                 const float mp = g_mp;
;                 const float M = fmaxf(mp, U);
;                 sU[lane] = uu; sM[lane] = M; sIW[lane] = expf(mp - M); sEMT[lane] = expf(-(b + M)); sRS[lane] = 0.f; sHS[lane] = 0.f;
.LBB0_1123:
	s_andn2_b64 vcc, exec, s[44:45]
	s_cbranch_vccnz .LBB0_1125
	s_waitcnt vmcnt(3)
	v_mul_f32_e64 v48, |v193|, s60
	v_rndne_f32_e32 v49, v48
	v_sub_f32_e32 v50, v48, v49
	v_fma_f32 v48, |v193|, s60, -v48
	s_mov_b32 s44, 0xb2a5705f
	v_fma_f32 v48, |v193|, s44, v48
	v_add_f32_e32 v48, v50, v48
	v_exp_f32_e32 v48, v48
	v_cvt_i32_f32_e32 v49, v49
	v_cmp_ngt_f32_e64 vcc, |v193|, s61
	s_mov_b32 s44, 0x3f2aaaab
	v_max_f32_e32 v50, v193, v193
	v_ldexp_f32 v48, v48, v49
	v_cndmask_b32_e32 v48, 0, v48, vcc
	v_cmp_nlt_f32_e64 vcc, |v193|, s62
	v_min_f32_e32 v50, 0, v50
	s_nop 0
	v_cndmask_b32_e32 v51, v190, v48, vcc
	v_add_f32_e32 v52, 1.0, v51
	v_add_f32_e32 v48, -1.0, v52
	v_sub_f32_e32 v49, v48, v52
	v_add_f32_e32 v49, 1.0, v49
	v_sub_f32_e32 v48, v51, v48
	v_add_f32_e32 v53, v48, v49
	v_frexp_mant_f32_e32 v54, v52
	v_cvt_f64_f32_e32 v[48:49], v52
	v_frexp_exp_i32_f64_e32 v48, v[48:49]
	v_cmp_gt_f32_e32 vcc, s44, v54
	s_mov_b32 s44, 0x3f317218
	s_nop 0
	v_subbrev_co_u32_e32 v48, vcc, 0, v48, vcc
	v_sub_u32_e32 v49, 0, v48
	v_ldexp_f32 v52, v52, v49
	v_ldexp_f32 v49, v53, v49
	v_add_f32_e32 v53, -1.0, v52
	v_add_f32_e32 v56, 1.0, v52
	v_add_f32_e32 v54, 1.0, v53
	v_add_f32_e32 v57, -1.0, v56
	v_sub_f32_e32 v54, v52, v54
	v_sub_f32_e32 v52, v52, v57
	v_add_f32_e32 v54, v49, v54
	v_add_f32_e32 v49, v49, v52
	v_add_f32_e32 v52, v56, v49
	v_rcp_f32_e32 v57, v52
	v_add_f32_e32 v55, v53, v54
	v_sub_f32_e32 v53, v53, v55
	v_add_f32_e32 v53, v54, v53
	v_sub_f32_e32 v54, v56, v52
	v_add_f32_e32 v49, v49, v54
	v_mul_f32_e32 v54, v55, v57
	v_mul_f32_e32 v56, v52, v54
	v_fma_f32 v58, v54, v52, -v56
	v_fmac_f32_e32 v58, v54, v49
	v_add_f32_e32 v59, v56, v58
	v_sub_f32_e32 v60, v55, v59
	v_sub_f32_e32 v55, v55, v60
	v_sub_f32_e32 v56, v59, v56
	v_sub_f32_e32 v55, v55, v59
	v_add_f32_e32 v53, v53, v55
	v_sub_f32_e32 v55, v56, v58
	v_add_f32_e32 v53, v55, v53
	v_add_f32_e32 v55, v60, v53
	v_mul_f32_e32 v56, v57, v55
	v_mul_f32_e32 v58, v52, v56
	v_fma_f32 v52, v56, v52, -v58
	v_fmac_f32_e32 v52, v56, v49
	v_sub_f32_e32 v49, v60, v55
	v_add_f32_e32 v49, v53, v49
	v_add_f32_e32 v53, v58, v52
	v_sub_f32_e32 v59, v55, v53
	v_sub_f32_e32 v55, v55, v59
	v_sub_f32_e32 v58, v53, v58
	v_sub_f32_e32 v53, v55, v53
	v_add_f32_e32 v49, v49, v53
	v_sub_f32_e32 v52, v58, v52
	v_cvt_f32_i32_e32 v48, v48
	v_add_f32_e32 v49, v52, v49
	v_add_f32_e32 v52, v54, v56
	v_add_f32_e32 v49, v59, v49
	v_sub_f32_e32 v53, v52, v54
	v_mul_f32_e32 v49, v57, v49
	v_sub_f32_e32 v53, v56, v53
	v_add_f32_e32 v49, v53, v49
	v_mul_f32_e32 v56, 0x3f317218, v48
	v_add_f32_e32 v53, v52, v49
	v_fma_f32 v57, v48, s44, -v56
	v_mul_f32_e32 v54, v53, v53
	v_fmac_f32_e32 v57, 0xb102e308, v48
	v_sub_f32_e32 v48, v53, v52
	v_fmamk_f32 v55, v54, 0x3e9b6dac, v169
	v_sub_f32_e32 v48, v49, v48
	v_add_f32_e32 v49, v56, v57
	v_fmaak_f32 v55, v54, v55, 0x3f2aaada
	v_sub_f32_e32 v52, v49, v56
	v_ldexp_f32 v56, v53, 1
	v_mul_f32_e32 v53, v53, v54
	v_mul_f32_e32 v53, v53, v55
	v_add_f32_e32 v54, v56, v53
	v_sub_f32_e32 v55, v54, v56
	v_ldexp_f32 v48, v48, 1
	v_sub_f32_e32 v53, v53, v55
	v_add_f32_e32 v48, v48, v53
	v_add_f32_e32 v53, v54, v48
	v_sub_f32_e32 v54, v53, v54
	v_sub_f32_e32 v48, v48, v54
	v_add_f32_e32 v54, v49, v53
	v_sub_f32_e32 v55, v54, v49
	v_sub_f32_e32 v56, v54, v55
	v_sub_f32_e32 v52, v57, v52
	v_sub_f32_e32 v49, v49, v56
	v_sub_f32_e32 v53, v53, v55
	v_add_f32_e32 v49, v53, v49
	v_add_f32_e32 v53, v52, v48
	v_sub_f32_e32 v55, v53, v52
	v_sub_f32_e32 v56, v53, v55
	v_sub_f32_e32 v52, v52, v56
	v_sub_f32_e32 v48, v48, v55
	v_add_f32_e32 v49, v53, v49
	v_add_f32_e32 v48, v48, v52
	v_add_f32_e32 v52, v54, v49
	v_sub_f32_e32 v53, v52, v54
	v_sub_f32_e32 v49, v49, v53
	v_add_f32_e32 v48, v48, v49
	s_mov_b32 s44, 0x7f800000
	v_add_f32_e32 v48, v52, v48
	v_cmp_neq_f32_e32 vcc, s44, v51
	s_mov_b32 s44, 0x33800000
	v_cndmask_b32_e32 v48, v190, v48, vcc
	v_cmp_lt_f32_e64 vcc, |v51|, s44
	s_nop 1
	v_cndmask_b32_e32 v48, v48, v51, vcc
	v_sub_f32_e32 v48, v50, v48
	s_nop 1
	v_add_f32_dpp v48, v48, v48 row_shr:1 row_mask:0xf bank_mask:0xf bound_ctrl:0
	s_nop 1
	v_add_f32_dpp v48, v48, v48 row_shr:2 row_mask:0xf bank_mask:0xf bound_ctrl:0
	s_nop 1
	v_add_f32_dpp v48, v48, v48 row_shr:4 row_mask:0xf bank_mask:0xf bound_ctrl:0
	s_nop 1
	v_add_f32_dpp v48, v48, v48 row_shr:8 row_mask:0xf bank_mask:0xf bound_ctrl:0
	s_nop 1
	v_add_f32_dpp v48, v48, v48 row_bcast:15 row_mask:0xa bank_mask:0xf
	s_nop 1
	v_add_f32_dpp v48, v48, v48 row_bcast:31 row_mask:0xc bank_mask:0xf
	v_sub_f32_e32 v55, v130, v48
	v_mov_b32_e32 v49, v55
	s_nop 1
	v_max_f32_dpp v49, v49, v49 row_shr:1 row_mask:0xf bank_mask:0xf
	s_nop 1
	v_max_f32_dpp v49, v49, v49 row_shr:2 row_mask:0xf bank_mask:0xf
	s_nop 1
	v_max_f32_dpp v49, v49, v49 row_shr:4 row_mask:0xf bank_mask:0xf
	s_nop 1
	v_max_f32_dpp v49, v49, v49 row_shr:8 row_mask:0xf bank_mask:0xf
	s_nop 1
	v_max_f32_dpp v49, v49, v49 row_bcast:15 row_mask:0xa bank_mask:0xf
	s_nop 1
	v_max_f32_dpp v49, v49, v49 row_bcast:31 row_mask:0xc bank_mask:0xf
	s_waitcnt vmcnt(2)
	v_max_f32_e32 v50, v111, v111
	v_max_f32_e32 v49, v50, v49
	v_sub_f32_e32 v50, v111, v49
	v_mul_f32_e32 v51, 0x3fb8aa3b, v50
	v_fma_f32 v52, v50, s63, -v51
	v_rndne_f32_e32 v53, v51
	v_fmac_f32_e32 v52, 0x32a5705f, v50
	v_sub_f32_e32 v51, v51, v53
	v_add_f32_e32 v51, v51, v52
	v_exp_f32_e32 v51, v51
	v_cvt_i32_f32_e32 v52, v53
	v_add_f32_e32 v48, v48, v49
	ds_write_b32 v91, v55
	ds_write_b32 v93, v49
	v_mul_f32_e32 v49, 0xbfb8aa3b, v48
	v_ldexp_f32 v51, v51, v52
	v_fma_f32 v52, v48, s60, -v49
	v_rndne_f32_e32 v53, v49
	v_fmac_f32_e32 v52, 0xb2a5705f, v48
	v_sub_f32_e32 v49, v49, v53
	v_add_f32_e32 v49, v49, v52
	v_exp_f32_e32 v49, v49
	v_cvt_i32_f32_e32 v52, v53
	v_cmp_ngt_f32_e32 vcc, s64, v50
	v_ldexp_f32 v49, v49, v52
	s_nop 0
	v_cndmask_b32_e32 v51, 0, v51, vcc
	v_cmp_nlt_f32_e32 vcc, s65, v50
	s_nop 1
	v_cndmask_b32_e32 v50, v190, v51, vcc
	v_cmp_nlt_f32_e32 vcc, s61, v48
	ds_write_b32 v94, v50
	s_nop 0
	v_cndmask_b32_e32 v49, 0, v49, vcc
	v_cmp_ngt_f32_e32 vcc, s62, v48
	s_nop 1
	v_cndmask_b32_e32 v48, v190, v49, vcc
	ds_write_b32 v95, v48
	ds_write_b32 v96, v81
	ds_write_b32 v97, v81
